# G1 K-loop: global loads via saddr + per-lane offsets (no per-K-step 64-bit VALU address arithmetic), scalar base advance
# speedup vs baseline: 1.1566x; 1.0063x over previous
; __device__ __forceinline__ int otid() { int t = threadIdx.x; asm volatile("" : "+v"(t)); return t; }
; __device__ __forceinline__ void gemm_core_big(const bf16_t* __restrict__ A, int lda, const bf16_t* __restrict__ Bt, int ldb,
;                                               int K, f32x4 (&acc)[8][4], char* smem) {
;   bf16_t* sA = (bf16_t*)smem;
;   bf16_t* sB = sA + 256 * LDS_STRIDE;
;   const int tid = otid(), lane = tid & 63, wave = tid >> 6;
;   const int wm = wave >> 1, wn = wave & 1;
;   const int lr = tid >> 3, lc = (tid & 7) * 8;
;   const bf16_t* ap = A + (size_t)lr * lda + lc;
;   const bf16_t* bp = Bt + (size_t)lr * ldb + lc;
;   const int nk = K >> 6;
;   const int fr = lane & 15, fq = (lane >> 4) * 8;
;   const int rswz = (fr >> 1) & 7, wswz = (lr >> 1) & 7;
;   const int fo0 = (((lane >> 4)) ^ rswz) * 8, fo1 = ((4 + (lane >> 4)) ^ rswz) * 8;
;   const bf16_t* cA = sA + (wm * 128 + fr) * LDS_STRIDE;
;   const bf16_t* cB = sB + (wn * 64 + fr) * LDS_STRIDE;
;   bf16_t* wA = sA + lr * LDS_STRIDE + (((tid & 7) ^ wswz) * 8);
;   bf16_t* wB = sB + lr * LDS_STRIDE + (((tid & 7) ^ wswz) * 8);
; __device__ __forceinline__ void phase_gemm_in(const Params& p, char* smem) {
;     ...
;     int mt, nt;
;     if (!tile_at(it, MT, NTn, mt, nt)) break;
;     f32x4 acc[8][4];
; #pragma unroll
;     for (int i = 0; i < 8; ++i)
; #pragma unroll
;       for (int j = 0; j < 4; ++j) acc[i][j] = (f32x4){0.f, 0.f, 0.f, 0.f};
;     gemm_core_big(H + (size_t)mt * 256 * 1024, 1024, W + (size_t)nt * 128 * 1024, 1024, 1024, acc, smem);
.LBB0_709:
	s_lshl_b32 s12, s23, s24
	s_add_i32 s12, s12, s22
	s_mul_i32 s14, s12, s16
	s_add_i32 s14, s14, s25
	s_cmpk_gt_i32 s14, 0x11c5
	s_mov_b64 s[12:13], -1
	s_cbranch_scc1 .LBB0_708
	s_mul_hi_i32 s12, s14, 0xea0ea0eb
	s_add_i32 s12, s12, s14
	s_lshr_b32 s13, s12, 31
	s_ashr_i32 s12, s12, 9
	s_add_i32 s12, s12, s13
	s_lshl_b32 s13, s12, 3
	s_sub_i32 s15, 0x41, s13
	s_min_u32 s15, s15, 8
	v_cvt_f32_ubyte0_e32 v0, s15
	v_rcp_iflag_f32_e32 v0, v0
	s_sub_i32 s26, 0, s15
	s_mulk_i32 s12, 0xfdd0
	s_add_i32 s12, s12, s14
	v_mul_f32_e32 v0, 0x4f7ffffe, v0
	v_cvt_u32_f32_e32 v0, v0
	s_abs_i32 s18, s12
	s_ashr_i32 s14, s12, 31
	v_readlane_b32 s0, v241, 11
	v_readfirstlane_b32 s27, v0
	s_mul_i32 s26, s26, s27
	s_mul_hi_u32 s26, s27, s26
	s_add_i32 s27, s27, s26
	s_mul_hi_u32 s27, s18, s27
	s_mul_i32 s26, s27, s15
	s_sub_i32 s18, s18, s26
	s_add_i32 s28, s27, 1
	s_sub_i32 s29, s18, s15
	s_cmp_ge_u32 s18, s15
	s_cselect_b32 s27, s28, s27
	s_cselect_b32 s18, s29, s18
	s_add_i32 s28, s27, 1
	s_cmp_ge_u32 s18, s15
	s_cselect_b32 s18, s28, s27
	s_xor_b32 s18, s18, s14
	s_sub_i32 s14, s18, s14
	s_add_i32 s12, s12, s13
	s_mul_i32 s13, s14, s15
	s_sub_i32 s12, s12, s13
	s_ashr_i32 s13, s12, 31
	s_lshl_b64 s[28:29], s[12:13], 19
	v_readlane_b32 s1, v241, 12
	s_add_u32 s28, s0, s28
	s_addc_u32 s29, s1, s29
	s_ashr_i32 s15, s14, 31
	v_mov_b32_e32 v8, v178
	s_lshl_b64 s[30:31], s[14:15], 18
	v_readlane_b32 s0, v244, 42
	s_add_u32 s30, s0, s30
	v_ashrrev_i32_e32 v4, 3, v8
	v_readlane_b32 s0, v244, 43
	v_ashrrev_i32_e32 v5, 31, v4
	s_addc_u32 s31, s0, s31
	v_lshlrev_b64 v[6:7], 11, v[4:5]
	v_lshlrev_b32_e32 v2, 4, v8
	v_lshrrev_b32_e32 v5, 4, v8
	v_lshl_add_u64 v[0:1], s[28:29], 0, v[6:7]
	v_and_b32_e32 v2, 0x70, v2
	v_lshl_add_u64 v[6:7], s[30:31], 0, v[6:7]
	v_xor_b32_e32 v10, v5, v8
	v_lshl_add_u64 v[0:1], v[0:1], 0, v[2:3]
	v_bfe_u32 v9, v8, 1, 3
	v_lshl_add_u64 v[132:133], v[6:7], 0, v[2:3]
	v_lshlrev_b32_e32 v2, 4, v10
	v_lshlrev_b32_e32 v7, 7, v8
	v_and_b32_e32 v2, 0x70, v2
	v_bitop3_b32 v5, v5, v9, 3 bitop3:0x6c
	v_bfe_u32 v6, v8, 4, 2
	v_and_b32_e32 v8, 0xffffc780, v7
	v_lshl_or_b32 v2, v4, 7, v2
	v_and_b32_e32 v4, 0x2780, v7
	v_lshlrev_b32_e32 v5, 4, v5
	s_waitcnt vmcnt(8)
	v_or_b32_e32 v140, v4, v5
	v_or_b32_e32 v141, v8, v5
	v_bitop3_b32 v5, v6, v9, 4 bitop3:0x36
	v_lshlrev_b32_e32 v5, 4, v5
	s_waitcnt vmcnt(4)
	v_mov_b32_e32 v28, 0
	s_mov_b32 s26, 1
	v_or_b32_e32 v142, v4, v5
	v_or_b32_e32 v143, v8, v5
	v_mov_b64_e32 v[134:135], v[0:1]
	v_mov_b64_e32 v[136:137], v[132:133]
	v_mov_b32_e32 v29, v28
	v_mov_b32_e32 v30, v28
	v_mov_b32_e32 v31, v28
	v_mov_b32_e32 v4, v28
	v_mov_b32_e32 v5, v28
	v_mov_b32_e32 v6, v28
	v_mov_b32_e32 v7, v28
	v_mov_b32_e32 v8, v28
	v_mov_b32_e32 v9, v28
	v_mov_b32_e32 v10, v28
	v_mov_b32_e32 v11, v28
	v_mov_b32_e32 v12, v28
	v_mov_b32_e32 v13, v28
	v_mov_b32_e32 v14, v28
	v_mov_b32_e32 v15, v28
	v_mov_b32_e32 v16, v28
	v_mov_b32_e32 v17, v28
	v_mov_b32_e32 v18, v28
	v_mov_b32_e32 v19, v28
	v_mov_b32_e32 v20, v28
	v_mov_b32_e32 v21, v28
	v_mov_b32_e32 v22, v28
	v_mov_b32_e32 v23, v28
	v_mov_b32_e32 v24, v28
	v_mov_b32_e32 v25, v28
	v_mov_b32_e32 v26, v28
	v_mov_b32_e32 v27, v28
	v_mov_b32_e32 v32, v28
	v_mov_b32_e32 v33, v28
	v_mov_b32_e32 v34, v28
	v_mov_b32_e32 v35, v28
	v_mov_b32_e32 v36, v28
	v_mov_b32_e32 v37, v28
	v_mov_b32_e32 v38, v28
	v_mov_b32_e32 v39, v28
	v_mov_b32_e32 v40, v28
	v_mov_b32_e32 v41, v28
	v_mov_b32_e32 v42, v28
	v_mov_b32_e32 v43, v28
	v_mov_b32_e32 v44, v28
	v_mov_b32_e32 v45, v28
	v_mov_b32_e32 v46, v28
	v_mov_b32_e32 v47, v28
	v_mov_b32_e32 v48, v28
	v_mov_b32_e32 v49, v28
	v_mov_b32_e32 v50, v28
	v_mov_b32_e32 v51, v28
	v_mov_b32_e32 v52, v28
	v_mov_b32_e32 v53, v28
	v_mov_b32_e32 v54, v28
	v_mov_b32_e32 v55, v28
	v_mov_b32_e32 v56, v28
	v_mov_b32_e32 v57, v28
	v_mov_b32_e32 v58, v28
	v_mov_b32_e32 v59, v28
	v_mov_b32_e32 v60, v28
	v_mov_b32_e32 v61, v28
	v_mov_b32_e32 v62, v28
	v_mov_b32_e32 v63, v28
	v_mov_b32_e32 v64, v28
	v_mov_b32_e32 v65, v28
	v_mov_b32_e32 v66, v28
	v_mov_b32_e32 v67, v28
	v_mov_b32_e32 v68, v28
	v_mov_b32_e32 v69, v28
	v_mov_b32_e32 v70, v28
	v_mov_b32_e32 v71, v28
	v_mov_b32_e32 v72, v28
	v_mov_b32_e32 v73, v28
	v_mov_b32_e32 v74, v28
	v_mov_b32_e32 v75, v28
	v_mov_b32_e32 v76, v28
	v_mov_b32_e32 v77, v28
	v_mov_b32_e32 v78, v28
	v_mov_b32_e32 v79, v28
	v_mov_b32_e32 v80, v28
	v_mov_b32_e32 v81, v28
	v_mov_b32_e32 v82, v28
	v_mov_b32_e32 v83, v28
	v_mov_b32_e32 v84, v28
	v_mov_b32_e32 v85, v28
	v_mov_b32_e32 v86, v28
	v_mov_b32_e32 v87, v28
	v_mov_b32_e32 v88, v28
	v_mov_b32_e32 v89, v28
	v_mov_b32_e32 v90, v28
	v_mov_b32_e32 v91, v28
	v_mov_b32_e32 v92, v28
	v_mov_b32_e32 v93, v28
	v_mov_b32_e32 v94, v28
	v_mov_b32_e32 v95, v28
	v_mov_b32_e32 v96, v28
	v_mov_b32_e32 v97, v28
	v_mov_b32_e32 v98, v28
	v_mov_b32_e32 v99, v28
	v_mov_b32_e32 v100, v28
	v_mov_b32_e32 v101, v28
	v_mov_b32_e32 v102, v28
	v_mov_b32_e32 v103, v28
	v_mov_b32_e32 v104, v28
	v_mov_b32_e32 v105, v28
	v_mov_b32_e32 v106, v28
	v_mov_b32_e32 v107, v28
	v_mov_b32_e32 v108, v28
	v_mov_b32_e32 v109, v28
	v_mov_b32_e32 v110, v28
	v_mov_b32_e32 v111, v28
	v_mov_b32_e32 v112, v28
	v_mov_b32_e32 v113, v28
	v_mov_b32_e32 v114, v28
	v_mov_b32_e32 v115, v28
	v_mov_b32_e32 v116, v28
	v_mov_b32_e32 v117, v28
	v_mov_b32_e32 v118, v28
	v_mov_b32_e32 v119, v28
	v_mov_b32_e32 v120, v28
	v_mov_b32_e32 v121, v28
	v_mov_b32_e32 v122, v28
	v_mov_b32_e32 v123, v28
	v_mov_b32_e32 v124, v28
	v_mov_b32_e32 v125, v28
	v_mov_b32_e32 v126, v28
	v_mov_b32_e32 v127, v28
	v_mov_b32_e32 v128, v28
	v_mov_b32_e32 v129, v28
	v_mov_b32_e32 v130, v28
	v_mov_b32_e32 v131, v28
	s_mov_b32 s0, 0x30000
	s_mov_b32 s1, 0x10000
	s_mov_b32 s15, 0x20000
	v_lshrrev_b32_e32 v232, 3, v178
	v_and_b32_e32 v233, 7, v178
	v_lshlrev_b32_e32 v232, 11, v232
	v_lshl_add_u32 v224, v233, 4, v232
	v_add_u32_e32 v225, 0x10000, v224
	v_add_u32_e32 v226, 0x20000, v224
	v_add_u32_e32 v227, 0x30000, v224
	v_add_u32_e32 v228, 0x40000, v224
	v_add_u32_e32 v229, 0x50000, v224
	v_add_u32_e32 v230, 0x60000, v224
	v_add_u32_e32 v231, 0x70000, v224
; __device__ __forceinline__ void gemm_core_big(const bf16_t* __restrict__ A, int lda, const bf16_t* __restrict__ Bt, int ldb,
;                                               int K, f32x4 (&acc)[8][4], char* smem) {
;     ...
;   for (int kt = 0; kt < nk; ++kt) {
;     __syncthreads();
; #pragma unroll
;     for (int i = 0; i < 8; ++i) *(u32x4*)(wA + 32 * i * LDS_STRIDE) = ra[i];
; #pragma unroll
;     for (int i = 0; i < 4; ++i) *(u32x4*)(wB + 32 * i * LDS_STRIDE) = rb[i];
;     __syncthreads();
;     {
;       const int k1 = min(kt + 1, nk - 1) << 6;
; #pragma unroll
;       for (int i = 0; i < 8; ++i) ra[i] = *(const u32x4*)(ap + (size_t)(32 * i) * lda + k1);
; #pragma unroll
;       for (int i = 0; i < 4; ++i) rb[i] = *(const u32x4*)(bp + (size_t)(32 * i) * ldb + k1);
;     }
; #pragma unroll
;     for (int ks = 0; ks < 2; ++ks) {
;       const int fo = ks ? fo1 : fo0;
;       bf16x8 bfr[4];
; #pragma unroll
;       for (int j = 0; j < 4; ++j) bfr[j] = *(const bf16x8*)(cB + j * 16 * LDS_STRIDE + fo);
; #pragma unroll
;       for (int i = 0; i < 8; ++i) {
;         const bf16x8 af = *(const bf16x8*)(cA + i * 16 * LDS_STRIDE + fo);
; #pragma unroll
;         for (int j = 0; j < 4; ++j)
;           acc[i][j] = __builtin_amdgcn_mfma_f32_16x16x32_bf16(bfr[j], af, acc[i][j], 0, 0, 0);
;       }
;     }
.LBB0_711:
	s_setprio 0
	global_load_dwordx4 v[144:147], v224, s[30:31]
	global_load_dwordx4 v[148:151], v224, s[28:29]
	global_load_dwordx4 v[134:137], v225, s[28:29]
	global_load_dwordx4 v[152:155], v226, s[28:29]
	global_load_dwordx4 v[156:159], v227, s[28:29]
	global_load_dwordx4 v[160:163], v228, s[28:29]
	global_load_dwordx4 v[164:167], v229, s[28:29]
	global_load_dwordx4 v[168:171], v230, s[28:29]
	global_load_dwordx4 v[172:175], v231, s[28:29]
	global_load_dwordx4 v[188:191], v225, s[30:31]
	global_load_dwordx4 v[192:195], v226, s[30:31]
	global_load_dwordx4 v[196:199], v227, s[30:31]
	s_add_u32 s28, s28, 0x80
	s_addc_u32 s29, s29, 0
	s_add_u32 s30, s30, 0x80
	s_addc_u32 s31, s31, 0
	s_barrier
	s_add_i32 s26, s26, 1
	s_lshl_b32 s18, s13, 7
	s_cmp_lg_u32 s26, 17
	s_waitcnt vmcnt(10)
	ds_write_b128 v2, v[148:151]
	ds_write_b128 v2, v[144:147] offset:32768
	s_waitcnt vmcnt(9)
	ds_write_b128 v2, v[134:137] offset:4096
	s_waitcnt vmcnt(8)
	ds_write_b128 v2, v[152:155] offset:8192
	s_waitcnt vmcnt(7)
	ds_write_b128 v2, v[156:159] offset:12288
	s_waitcnt vmcnt(6)
	ds_write_b128 v2, v[160:163] offset:16384
	s_waitcnt vmcnt(5)
	ds_write_b128 v2, v[164:167] offset:20480
	s_waitcnt vmcnt(4)
	ds_write_b128 v2, v[168:171] offset:24576
	s_waitcnt vmcnt(3)
	ds_write_b128 v2, v[172:175] offset:28672
	s_waitcnt vmcnt(2)
	ds_write_b128 v2, v[188:191] offset:36864
	s_waitcnt vmcnt(1)
	ds_write_b128 v2, v[192:195] offset:40960
	s_waitcnt vmcnt(0)
	ds_write_b128 v2, v[196:199] offset:45056
	s_waitcnt lgkmcnt(0)
	s_barrier
	ds_read_b128 v[134:137], v140 offset:32768
	ds_read_b128 v[144:147], v140 offset:34816
	ds_read_b128 v[156:159], v140 offset:36864
	ds_read_b128 v[160:163], v140 offset:38912
	ds_read_b128 v[148:151], v141 offset:0
	ds_read_b128 v[152:155], v141 offset:2048
	ds_read_b128 v[216:219], v141 offset:4096
	ds_read_b128 v[220:223], v141 offset:6144
	s_setprio 1
	s_waitcnt lgkmcnt(3)
	v_mfma_f32_16x16x32_bf16 v[128:131], v[134:137], v[148:151], v[128:131]
	v_mfma_f32_16x16x32_bf16 v[124:127], v[144:147], v[148:151], v[124:127]
	v_mfma_f32_16x16x32_bf16 v[120:123], v[156:159], v[148:151], v[120:123]
	v_mfma_f32_16x16x32_bf16 v[116:119], v[160:163], v[148:151], v[116:119]
	s_waitcnt lgkmcnt(2)
	v_mfma_f32_16x16x32_bf16 v[112:115], v[134:137], v[152:155], v[112:115]
	v_mfma_f32_16x16x32_bf16 v[108:111], v[144:147], v[152:155], v[108:111]
	v_mfma_f32_16x16x32_bf16 v[104:107], v[156:159], v[152:155], v[104:107]
	v_mfma_f32_16x16x32_bf16 v[100:103], v[160:163], v[152:155], v[100:103]
	ds_read_b128 v[148:151], v141 offset:8192
	ds_read_b128 v[152:155], v141 offset:10240
	s_waitcnt lgkmcnt(3)
	v_mfma_f32_16x16x32_bf16 v[96:99], v[134:137], v[216:219], v[96:99]
	v_mfma_f32_16x16x32_bf16 v[92:95], v[144:147], v[216:219], v[92:95]
	v_mfma_f32_16x16x32_bf16 v[88:91], v[156:159], v[216:219], v[88:91]
	v_mfma_f32_16x16x32_bf16 v[84:87], v[160:163], v[216:219], v[84:87]
	s_waitcnt lgkmcnt(2)
	v_mfma_f32_16x16x32_bf16 v[80:83], v[134:137], v[220:223], v[80:83]
	v_mfma_f32_16x16x32_bf16 v[76:79], v[144:147], v[220:223], v[76:79]
	v_mfma_f32_16x16x32_bf16 v[72:75], v[156:159], v[220:223], v[72:75]
	v_mfma_f32_16x16x32_bf16 v[68:71], v[160:163], v[220:223], v[68:71]
	ds_read_b128 v[216:219], v141 offset:12288
	ds_read_b128 v[220:223], v141 offset:14336
	ds_read_b128 v[200:203], v142 offset:32768
	ds_read_b128 v[204:207], v142 offset:34816
	ds_read_b128 v[208:211], v142 offset:36864
	ds_read_b128 v[212:215], v142 offset:38912
	s_waitcnt lgkmcnt(7)
	v_mfma_f32_16x16x32_bf16 v[64:67], v[134:137], v[148:151], v[64:67]
	v_mfma_f32_16x16x32_bf16 v[60:63], v[144:147], v[148:151], v[60:63]
	v_mfma_f32_16x16x32_bf16 v[56:59], v[156:159], v[148:151], v[56:59]
	v_mfma_f32_16x16x32_bf16 v[52:55], v[160:163], v[148:151], v[52:55]
	s_waitcnt lgkmcnt(6)
	v_mfma_f32_16x16x32_bf16 v[48:51], v[134:137], v[152:155], v[48:51]
	v_mfma_f32_16x16x32_bf16 v[44:47], v[144:147], v[152:155], v[44:47]
	v_mfma_f32_16x16x32_bf16 v[40:43], v[156:159], v[152:155], v[40:43]
	v_mfma_f32_16x16x32_bf16 v[36:39], v[160:163], v[152:155], v[36:39]
	ds_read_b128 v[148:151], v143 offset:0
	ds_read_b128 v[152:155], v143 offset:2048
	s_waitcnt lgkmcnt(7)
	v_mfma_f32_16x16x32_bf16 v[32:35], v[134:137], v[216:219], v[32:35]
	v_mfma_f32_16x16x32_bf16 v[24:27], v[144:147], v[216:219], v[24:27]
	v_mfma_f32_16x16x32_bf16 v[20:23], v[156:159], v[216:219], v[20:23]
	v_mfma_f32_16x16x32_bf16 v[16:19], v[160:163], v[216:219], v[16:19]
	s_waitcnt lgkmcnt(6)
	v_mfma_f32_16x16x32_bf16 v[12:15], v[134:137], v[220:223], v[12:15]
	v_mfma_f32_16x16x32_bf16 v[8:11], v[144:147], v[220:223], v[8:11]
	v_mfma_f32_16x16x32_bf16 v[4:7], v[156:159], v[220:223], v[4:7]
	v_mfma_f32_16x16x32_bf16 v[28:31], v[160:163], v[220:223], v[28:31]
	ds_read_b128 v[216:219], v143 offset:4096
	ds_read_b128 v[220:223], v143 offset:6144
	s_waitcnt lgkmcnt(3)
	v_mfma_f32_16x16x32_bf16 v[128:131], v[200:203], v[148:151], v[128:131]
	v_mfma_f32_16x16x32_bf16 v[124:127], v[204:207], v[148:151], v[124:127]
	v_mfma_f32_16x16x32_bf16 v[120:123], v[208:211], v[148:151], v[120:123]
	v_mfma_f32_16x16x32_bf16 v[116:119], v[212:215], v[148:151], v[116:119]
	s_waitcnt lgkmcnt(2)
	v_mfma_f32_16x16x32_bf16 v[112:115], v[200:203], v[152:155], v[112:115]
	v_mfma_f32_16x16x32_bf16 v[108:111], v[204:207], v[152:155], v[108:111]
	v_mfma_f32_16x16x32_bf16 v[104:107], v[208:211], v[152:155], v[104:107]
	v_mfma_f32_16x16x32_bf16 v[100:103], v[212:215], v[152:155], v[100:103]
	ds_read_b128 v[148:151], v143 offset:8192
	ds_read_b128 v[152:155], v143 offset:10240
	s_waitcnt lgkmcnt(3)
; __device__ __forceinline__ unsigned pack2(float a, float b) { return (unsigned)f2bf(a) | ((unsigned)f2bf(b) << 16); }
; __device__ __forceinline__ void gemm_core_big(const bf16_t* __restrict__ A, int lda, const bf16_t* __restrict__ Bt, int ldb,
;                                               int K, f32x4 (&acc)[8][4], char* smem) {
;     ...
; #pragma unroll
;     for (int ks = 0; ks < 2; ++ks) {
;       const int fo = ks ? fo1 : fo0;
;       bf16x8 bfr[4];
; #pragma unroll
;       for (int j = 0; j < 4; ++j) bfr[j] = *(const bf16x8*)(cB + j * 16 * LDS_STRIDE + fo);
; #pragma unroll
;       for (int i = 0; i < 8; ++i) {
;         const bf16x8 af = *(const bf16x8*)(cA + i * 16 * LDS_STRIDE + fo);
; #pragma unroll
;         for (int j = 0; j < 4; ++j)
;           acc[i][j] = __builtin_amdgcn_mfma_f32_16x16x32_bf16(bfr[j], af, acc[i][j], 0, 0, 0);
;       }
;     }
; __device__ __forceinline__ void phase_gemm_in(const Params& p, char* smem) {
;     ...
;     bf16_t* dst; int ldd, ncol0;
;     if (nt < PRE_W / 128) { dst = PRE; ldd = PRE_W; ncol0 = nt * 128; }
;     else { dst = POST; ldd = POST_W; ncol0 = (nt - PRE_W / 128) * 128; }
; #pragma unroll
;     for (int i = 0; i < 8; ++i) {
;       const int m = mt * 256 + wm * 128 + i * 16 + (lane & 15);
; #pragma unroll
;       for (int j = 0; j < 4; ++j) {
;         const int n = ncol0 + wn * 64 + j * 16 + (lane >> 4) * 4;
;         uint2 o;
;         o.x = pack2(acc[i][j][0], acc[i][j][1]);
;         o.y = pack2(acc[i][j][2], acc[i][j][3]);
;         *(uint2*)(dst + (size_t)m * ldd + n) = o;
;       }
;     }
	v_mfma_f32_16x16x32_bf16 v[96:99], v[200:203], v[216:219], v[96:99]
	v_mfma_f32_16x16x32_bf16 v[92:95], v[204:207], v[216:219], v[92:95]
	v_mfma_f32_16x16x32_bf16 v[88:91], v[208:211], v[216:219], v[88:91]
	v_mfma_f32_16x16x32_bf16 v[84:87], v[212:215], v[216:219], v[84:87]
	s_waitcnt lgkmcnt(2)
	v_mfma_f32_16x16x32_bf16 v[80:83], v[200:203], v[220:223], v[80:83]
	v_mfma_f32_16x16x32_bf16 v[76:79], v[204:207], v[220:223], v[76:79]
	v_mfma_f32_16x16x32_bf16 v[72:75], v[208:211], v[220:223], v[72:75]
	v_mfma_f32_16x16x32_bf16 v[68:71], v[212:215], v[220:223], v[68:71]
	ds_read_b128 v[216:219], v143 offset:12288
	ds_read_b128 v[220:223], v143 offset:14336
	s_waitcnt lgkmcnt(3)
	v_mfma_f32_16x16x32_bf16 v[64:67], v[200:203], v[148:151], v[64:67]
	v_mfma_f32_16x16x32_bf16 v[60:63], v[204:207], v[148:151], v[60:63]
	v_mfma_f32_16x16x32_bf16 v[56:59], v[208:211], v[148:151], v[56:59]
	v_mfma_f32_16x16x32_bf16 v[52:55], v[212:215], v[148:151], v[52:55]
	s_waitcnt lgkmcnt(2)
	v_mfma_f32_16x16x32_bf16 v[48:51], v[200:203], v[152:155], v[48:51]
	v_mfma_f32_16x16x32_bf16 v[44:47], v[204:207], v[152:155], v[44:47]
	v_mfma_f32_16x16x32_bf16 v[40:43], v[208:211], v[152:155], v[40:43]
	v_mfma_f32_16x16x32_bf16 v[36:39], v[212:215], v[152:155], v[36:39]
	s_waitcnt lgkmcnt(1)
	v_mfma_f32_16x16x32_bf16 v[32:35], v[200:203], v[216:219], v[32:35]
	v_mfma_f32_16x16x32_bf16 v[24:27], v[204:207], v[216:219], v[24:27]
	v_mfma_f32_16x16x32_bf16 v[20:23], v[208:211], v[216:219], v[20:23]
	v_mfma_f32_16x16x32_bf16 v[16:19], v[212:215], v[216:219], v[16:19]
	s_waitcnt lgkmcnt(0)
	v_mfma_f32_16x16x32_bf16 v[12:15], v[200:203], v[220:223], v[12:15]
	v_mfma_f32_16x16x32_bf16 v[8:11], v[204:207], v[220:223], v[8:11]
	v_mfma_f32_16x16x32_bf16 v[4:7], v[208:211], v[220:223], v[4:7]
	v_mfma_f32_16x16x32_bf16 v[28:31], v[212:215], v[220:223], v[28:31]
	s_cbranch_scc1 .LBB0_711
	s_setprio 0
	s_lshl_b32 s13, s14, 7
	s_add_i32 s15, s13, 0xffffef00
	s_cmp_lt_i32 s14, 34
	s_mov_b32 s14, 0x4100000
	s_cselect_b32 s18, s14, 0xcb20000
	s_movk_i32 s0, 0x1200
	s_cselect_b32 s15, s13, s15
	v_and_b32_sdwa v134, v130, v183 dst_sel:DWORD dst_unused:UNUSED_PAD src0_sel:WORD_1 src1_sel:DWORD
	v_and_b32_sdwa v135, v128, v183 dst_sel:DWORD dst_unused:UNUSED_PAD src0_sel:WORD_1 src1_sel:DWORD
	s_cselect_b32 s14, 0x1100, s0
	v_lshl_add_u32 v2, s12, 8, v138
	s_add_u32 s12, s10, s18
	v_or_b32_e32 v0, s15, v139
	v_add3_u32 v128, v128, v135, s37
	v_add3_u32 v130, v130, v134, s37
	v_and_b32_sdwa v134, v131, v183 dst_sel:DWORD dst_unused:UNUSED_PAD src0_sel:WORD_1 src1_sel:DWORD
	v_and_b32_sdwa v135, v129, v183 dst_sel:DWORD dst_unused:UNUSED_PAD src0_sel:WORD_1 src1_sel:DWORD
	s_addc_u32 s13, s11, 0
	v_mad_i64_i32 v[132:133], s[26:27], s14, v2, 0
	v_ashrrev_i32_e32 v1, 31, v0
	v_add3_u32 v131, v131, v134, s37
	v_add3_u32 v129, v129, v135, s37
	v_lshl_add_u64 v[132:133], v[132:133], 1, s[12:13]
	v_lshlrev_b64 v[0:1], 1, v[0:1]
	v_and_b32_e32 v131, 0xffff0000, v131
	v_and_b32_e32 v134, 0xffff0000, v129
	v_lshl_add_u64 v[132:133], v[132:133], 0, v[0:1]
	v_or_b32_sdwa v129, v131, v130 dst_sel:DWORD dst_unused:UNUSED_PAD src0_sel:DWORD src1_sel:WORD_1
	v_or_b32_sdwa v128, v134, v128 dst_sel:DWORD dst_unused:UNUSED_PAD src0_sel:DWORD src1_sel:WORD_1
	global_store_dwordx2 v[132:133], v[128:129], off
	v_and_b32_sdwa v128, v126, v183 dst_sel:DWORD dst_unused:UNUSED_PAD src0_sel:WORD_1 src1_sel:DWORD
	v_and_b32_sdwa v129, v124, v183 dst_sel:DWORD dst_unused:UNUSED_PAD src0_sel:WORD_1 src1_sel:DWORD
	v_add3_u32 v124, v124, v129, s37
	v_add3_u32 v126, v126, v128, s37
	v_and_b32_sdwa v128, v127, v183 dst_sel:DWORD dst_unused:UNUSED_PAD src0_sel:WORD_1 src1_sel:DWORD
	v_and_b32_sdwa v129, v125, v183 dst_sel:DWORD dst_unused:UNUSED_PAD src0_sel:WORD_1 src1_sel:DWORD
	v_add3_u32 v127, v127, v128, s37
	v_add3_u32 v125, v125, v129, s37
	v_and_b32_e32 v127, 0xffff0000, v127
	v_and_b32_e32 v128, 0xffff0000, v125
	v_or_b32_sdwa v125, v127, v126 dst_sel:DWORD dst_unused:UNUSED_PAD src0_sel:DWORD src1_sel:WORD_1
	v_or_b32_sdwa v124, v128, v124 dst_sel:DWORD dst_unused:UNUSED_PAD src0_sel:DWORD src1_sel:WORD_1
	global_store_dwordx2 v[132:133], v[124:125], off offset:32
	v_and_b32_sdwa v124, v122, v183 dst_sel:DWORD dst_unused:UNUSED_PAD src0_sel:WORD_1 src1_sel:DWORD
	v_and_b32_sdwa v125, v120, v183 dst_sel:DWORD dst_unused:UNUSED_PAD src0_sel:WORD_1 src1_sel:DWORD
	v_add3_u32 v120, v120, v125, s37
	v_add3_u32 v122, v122, v124, s37
	v_and_b32_sdwa v124, v123, v183 dst_sel:DWORD dst_unused:UNUSED_PAD src0_sel:WORD_1 src1_sel:DWORD
	v_and_b32_sdwa v125, v121, v183 dst_sel:DWORD dst_unused:UNUSED_PAD src0_sel:WORD_1 src1_sel:DWORD
	v_add3_u32 v123, v123, v124, s37
	v_add3_u32 v121, v121, v125, s37
	v_and_b32_e32 v123, 0xffff0000, v123
	v_and_b32_e32 v124, 0xffff0000, v121
	v_or_b32_sdwa v121, v123, v122 dst_sel:DWORD dst_unused:UNUSED_PAD src0_sel:DWORD src1_sel:WORD_1
	v_or_b32_sdwa v120, v124, v120 dst_sel:DWORD dst_unused:UNUSED_PAD src0_sel:DWORD src1_sel:WORD_1
	global_store_dwordx2 v[132:133], v[120:121], off offset:64
	v_and_b32_sdwa v120, v118, v183 dst_sel:DWORD dst_unused:UNUSED_PAD src0_sel:WORD_1 src1_sel:DWORD
	v_and_b32_sdwa v121, v116, v183 dst_sel:DWORD dst_unused:UNUSED_PAD src0_sel:WORD_1 src1_sel:DWORD
	v_add3_u32 v116, v116, v121, s37
	v_add3_u32 v118, v118, v120, s37
	v_and_b32_sdwa v120, v119, v183 dst_sel:DWORD dst_unused:UNUSED_PAD src0_sel:WORD_1 src1_sel:DWORD
	v_and_b32_sdwa v121, v117, v183 dst_sel:DWORD dst_unused:UNUSED_PAD src0_sel:WORD_1 src1_sel:DWORD
	v_add3_u32 v119, v119, v120, s37
	v_add3_u32 v117, v117, v121, s37
	v_and_b32_e32 v119, 0xffff0000, v119
	v_and_b32_e32 v120, 0xffff0000, v117
; __device__ __forceinline__ unsigned pack2(float a, float b) { return (unsigned)f2bf(a) | ((unsigned)f2bf(b) << 16); }
; __device__ __forceinline__ void phase_gemm_in(const Params& p, char* smem) {
;     ...
; #pragma unroll
;     for (int i = 0; i < 8; ++i) {
;       const int m = mt * 256 + wm * 128 + i * 16 + (lane & 15);
; #pragma unroll
;       for (int j = 0; j < 4; ++j) {
;         const int n = ncol0 + wn * 64 + j * 16 + (lane >> 4) * 4;
;         uint2 o;
;         o.x = pack2(acc[i][j][0], acc[i][j][1]);
;         o.y = pack2(acc[i][j][2], acc[i][j][3]);
;         *(uint2*)(dst + (size_t)m * ldd + n) = o;
;       }
;     }
	v_or_b32_sdwa v117, v119, v118 dst_sel:DWORD dst_unused:UNUSED_PAD src0_sel:DWORD src1_sel:WORD_1
	v_or_b32_sdwa v116, v120, v116 dst_sel:DWORD dst_unused:UNUSED_PAD src0_sel:DWORD src1_sel:WORD_1
	v_and_b32_sdwa v118, v114, v183 dst_sel:DWORD dst_unused:UNUSED_PAD src0_sel:WORD_1 src1_sel:DWORD
	v_and_b32_sdwa v119, v112, v183 dst_sel:DWORD dst_unused:UNUSED_PAD src0_sel:WORD_1 src1_sel:DWORD
	global_store_dwordx2 v[132:133], v[116:117], off offset:96
	v_or_b32_e32 v116, 16, v2
	v_add3_u32 v112, v112, v119, s37
	v_add3_u32 v114, v114, v118, s37
	v_and_b32_sdwa v118, v115, v183 dst_sel:DWORD dst_unused:UNUSED_PAD src0_sel:WORD_1 src1_sel:DWORD
	v_and_b32_sdwa v119, v113, v183 dst_sel:DWORD dst_unused:UNUSED_PAD src0_sel:WORD_1 src1_sel:DWORD
	v_mad_i64_i32 v[116:117], s[26:27], s14, v116, 0
	v_add3_u32 v115, v115, v118, s37
	v_add3_u32 v113, v113, v119, s37
	v_lshl_add_u64 v[116:117], v[116:117], 1, s[12:13]
	v_and_b32_e32 v115, 0xffff0000, v115
	v_and_b32_e32 v118, 0xffff0000, v113
	v_lshl_add_u64 v[116:117], v[116:117], 0, v[0:1]
	v_or_b32_sdwa v113, v115, v114 dst_sel:DWORD dst_unused:UNUSED_PAD src0_sel:DWORD src1_sel:WORD_1
	v_or_b32_sdwa v112, v118, v112 dst_sel:DWORD dst_unused:UNUSED_PAD src0_sel:DWORD src1_sel:WORD_1
	global_store_dwordx2 v[116:117], v[112:113], off
	v_and_b32_sdwa v112, v110, v183 dst_sel:DWORD dst_unused:UNUSED_PAD src0_sel:WORD_1 src1_sel:DWORD
	v_and_b32_sdwa v113, v108, v183 dst_sel:DWORD dst_unused:UNUSED_PAD src0_sel:WORD_1 src1_sel:DWORD
	v_add3_u32 v108, v108, v113, s37
	v_add3_u32 v110, v110, v112, s37
	v_and_b32_sdwa v112, v111, v183 dst_sel:DWORD dst_unused:UNUSED_PAD src0_sel:WORD_1 src1_sel:DWORD
	v_and_b32_sdwa v113, v109, v183 dst_sel:DWORD dst_unused:UNUSED_PAD src0_sel:WORD_1 src1_sel:DWORD
	v_add3_u32 v111, v111, v112, s37
	v_add3_u32 v109, v109, v113, s37
	v_and_b32_e32 v111, 0xffff0000, v111
	v_and_b32_e32 v112, 0xffff0000, v109
	v_or_b32_sdwa v109, v111, v110 dst_sel:DWORD dst_unused:UNUSED_PAD src0_sel:DWORD src1_sel:WORD_1
	v_or_b32_sdwa v108, v112, v108 dst_sel:DWORD dst_unused:UNUSED_PAD src0_sel:DWORD src1_sel:WORD_1
	global_store_dwordx2 v[116:117], v[108:109], off offset:32
	v_and_b32_sdwa v108, v106, v183 dst_sel:DWORD dst_unused:UNUSED_PAD src0_sel:WORD_1 src1_sel:DWORD
	v_and_b32_sdwa v109, v104, v183 dst_sel:DWORD dst_unused:UNUSED_PAD src0_sel:WORD_1 src1_sel:DWORD
	v_add3_u32 v104, v104, v109, s37
	v_add3_u32 v106, v106, v108, s37
	v_and_b32_sdwa v108, v107, v183 dst_sel:DWORD dst_unused:UNUSED_PAD src0_sel:WORD_1 src1_sel:DWORD
	v_and_b32_sdwa v109, v105, v183 dst_sel:DWORD dst_unused:UNUSED_PAD src0_sel:WORD_1 src1_sel:DWORD
	v_add3_u32 v107, v107, v108, s37
	v_add3_u32 v105, v105, v109, s37
	v_and_b32_e32 v107, 0xffff0000, v107
	v_and_b32_e32 v108, 0xffff0000, v105
	v_or_b32_sdwa v105, v107, v106 dst_sel:DWORD dst_unused:UNUSED_PAD src0_sel:DWORD src1_sel:WORD_1
	v_or_b32_sdwa v104, v108, v104 dst_sel:DWORD dst_unused:UNUSED_PAD src0_sel:DWORD src1_sel:WORD_1
	global_store_dwordx2 v[116:117], v[104:105], off offset:64
	v_and_b32_sdwa v104, v102, v183 dst_sel:DWORD dst_unused:UNUSED_PAD src0_sel:WORD_1 src1_sel:DWORD
	v_and_b32_sdwa v105, v100, v183 dst_sel:DWORD dst_unused:UNUSED_PAD src0_sel:WORD_1 src1_sel:DWORD
	v_add3_u32 v100, v100, v105, s37
	v_add3_u32 v102, v102, v104, s37
	v_and_b32_sdwa v104, v103, v183 dst_sel:DWORD dst_unused:UNUSED_PAD src0_sel:WORD_1 src1_sel:DWORD
	v_and_b32_sdwa v105, v101, v183 dst_sel:DWORD dst_unused:UNUSED_PAD src0_sel:WORD_1 src1_sel:DWORD
	v_add3_u32 v103, v103, v104, s37
	v_add3_u32 v101, v101, v105, s37
	v_and_b32_e32 v103, 0xffff0000, v103
	v_and_b32_e32 v104, 0xffff0000, v101
	v_or_b32_sdwa v101, v103, v102 dst_sel:DWORD dst_unused:UNUSED_PAD src0_sel:DWORD src1_sel:WORD_1
	v_or_b32_sdwa v100, v104, v100 dst_sel:DWORD dst_unused:UNUSED_PAD src0_sel:DWORD src1_sel:WORD_1
	v_and_b32_sdwa v102, v98, v183 dst_sel:DWORD dst_unused:UNUSED_PAD src0_sel:WORD_1 src1_sel:DWORD
	v_and_b32_sdwa v103, v96, v183 dst_sel:DWORD dst_unused:UNUSED_PAD src0_sel:WORD_1 src1_sel:DWORD
	global_store_dwordx2 v[116:117], v[100:101], off offset:96
	v_or_b32_e32 v100, 32, v2
	v_add3_u32 v96, v96, v103, s37
	v_add3_u32 v98, v98, v102, s37
	v_and_b32_sdwa v102, v99, v183 dst_sel:DWORD dst_unused:UNUSED_PAD src0_sel:WORD_1 src1_sel:DWORD
	v_and_b32_sdwa v103, v97, v183 dst_sel:DWORD dst_unused:UNUSED_PAD src0_sel:WORD_1 src1_sel:DWORD
	v_mad_i64_i32 v[100:101], s[26:27], s14, v100, 0
	v_add3_u32 v99, v99, v102, s37
	v_add3_u32 v97, v97, v103, s37
	v_lshl_add_u64 v[100:101], v[100:101], 1, s[12:13]
	v_and_b32_e32 v99, 0xffff0000, v99
	v_and_b32_e32 v102, 0xffff0000, v97
	v_lshl_add_u64 v[100:101], v[100:101], 0, v[0:1]
	v_or_b32_sdwa v97, v99, v98 dst_sel:DWORD dst_unused:UNUSED_PAD src0_sel:DWORD src1_sel:WORD_1
	v_or_b32_sdwa v96, v102, v96 dst_sel:DWORD dst_unused:UNUSED_PAD src0_sel:DWORD src1_sel:WORD_1
	global_store_dwordx2 v[100:101], v[96:97], off
	v_and_b32_sdwa v96, v94, v183 dst_sel:DWORD dst_unused:UNUSED_PAD src0_sel:WORD_1 src1_sel:DWORD
	v_and_b32_sdwa v97, v92, v183 dst_sel:DWORD dst_unused:UNUSED_PAD src0_sel:WORD_1 src1_sel:DWORD
	v_add3_u32 v92, v92, v97, s37
	v_add3_u32 v94, v94, v96, s37
	v_and_b32_sdwa v96, v95, v183 dst_sel:DWORD dst_unused:UNUSED_PAD src0_sel:WORD_1 src1_sel:DWORD
	v_and_b32_sdwa v97, v93, v183 dst_sel:DWORD dst_unused:UNUSED_PAD src0_sel:WORD_1 src1_sel:DWORD
	v_add3_u32 v95, v95, v96, s37
	v_add3_u32 v93, v93, v97, s37
	v_and_b32_e32 v95, 0xffff0000, v95
	v_and_b32_e32 v96, 0xffff0000, v93
	v_or_b32_sdwa v93, v95, v94 dst_sel:DWORD dst_unused:UNUSED_PAD src0_sel:DWORD src1_sel:WORD_1
; __device__ __forceinline__ unsigned pack2(float a, float b) { return (unsigned)f2bf(a) | ((unsigned)f2bf(b) << 16); }
; __device__ __forceinline__ void phase_gemm_in(const Params& p, char* smem) {
;     ...
; #pragma unroll
;     for (int i = 0; i < 8; ++i) {
;       const int m = mt * 256 + wm * 128 + i * 16 + (lane & 15);
; #pragma unroll
;       for (int j = 0; j < 4; ++j) {
;         const int n = ncol0 + wn * 64 + j * 16 + (lane >> 4) * 4;
;         uint2 o;
;         o.x = pack2(acc[i][j][0], acc[i][j][1]);
;         o.y = pack2(acc[i][j][2], acc[i][j][3]);
;         *(uint2*)(dst + (size_t)m * ldd + n) = o;
;       }
;     }
	v_or_b32_sdwa v92, v96, v92 dst_sel:DWORD dst_unused:UNUSED_PAD src0_sel:DWORD src1_sel:WORD_1
	global_store_dwordx2 v[100:101], v[92:93], off offset:32
	v_and_b32_sdwa v92, v90, v183 dst_sel:DWORD dst_unused:UNUSED_PAD src0_sel:WORD_1 src1_sel:DWORD
	v_and_b32_sdwa v93, v88, v183 dst_sel:DWORD dst_unused:UNUSED_PAD src0_sel:WORD_1 src1_sel:DWORD
	v_add3_u32 v88, v88, v93, s37
	v_add3_u32 v90, v90, v92, s37
	v_and_b32_sdwa v92, v91, v183 dst_sel:DWORD dst_unused:UNUSED_PAD src0_sel:WORD_1 src1_sel:DWORD
	v_and_b32_sdwa v93, v89, v183 dst_sel:DWORD dst_unused:UNUSED_PAD src0_sel:WORD_1 src1_sel:DWORD
	v_add3_u32 v91, v91, v92, s37
	v_add3_u32 v89, v89, v93, s37
	v_and_b32_e32 v91, 0xffff0000, v91
	v_and_b32_e32 v92, 0xffff0000, v89
	v_or_b32_sdwa v89, v91, v90 dst_sel:DWORD dst_unused:UNUSED_PAD src0_sel:DWORD src1_sel:WORD_1
	v_or_b32_sdwa v88, v92, v88 dst_sel:DWORD dst_unused:UNUSED_PAD src0_sel:DWORD src1_sel:WORD_1
	global_store_dwordx2 v[100:101], v[88:89], off offset:64
	v_and_b32_sdwa v88, v86, v183 dst_sel:DWORD dst_unused:UNUSED_PAD src0_sel:WORD_1 src1_sel:DWORD
	v_and_b32_sdwa v89, v84, v183 dst_sel:DWORD dst_unused:UNUSED_PAD src0_sel:WORD_1 src1_sel:DWORD
	v_add3_u32 v84, v84, v89, s37
	v_add3_u32 v86, v86, v88, s37
	v_and_b32_sdwa v88, v87, v183 dst_sel:DWORD dst_unused:UNUSED_PAD src0_sel:WORD_1 src1_sel:DWORD
	v_and_b32_sdwa v89, v85, v183 dst_sel:DWORD dst_unused:UNUSED_PAD src0_sel:WORD_1 src1_sel:DWORD
	v_add3_u32 v87, v87, v88, s37
	v_add3_u32 v85, v85, v89, s37
	v_and_b32_e32 v87, 0xffff0000, v87
	v_and_b32_e32 v88, 0xffff0000, v85
	v_or_b32_sdwa v85, v87, v86 dst_sel:DWORD dst_unused:UNUSED_PAD src0_sel:DWORD src1_sel:WORD_1
	v_or_b32_sdwa v84, v88, v84 dst_sel:DWORD dst_unused:UNUSED_PAD src0_sel:DWORD src1_sel:WORD_1
	v_and_b32_sdwa v86, v82, v183 dst_sel:DWORD dst_unused:UNUSED_PAD src0_sel:WORD_1 src1_sel:DWORD
	v_and_b32_sdwa v87, v80, v183 dst_sel:DWORD dst_unused:UNUSED_PAD src0_sel:WORD_1 src1_sel:DWORD
	global_store_dwordx2 v[100:101], v[84:85], off offset:96
	v_or_b32_e32 v84, 48, v2
	v_add3_u32 v80, v80, v87, s37
	v_add3_u32 v82, v82, v86, s37
	v_and_b32_sdwa v86, v83, v183 dst_sel:DWORD dst_unused:UNUSED_PAD src0_sel:WORD_1 src1_sel:DWORD
	v_and_b32_sdwa v87, v81, v183 dst_sel:DWORD dst_unused:UNUSED_PAD src0_sel:WORD_1 src1_sel:DWORD
	v_mad_i64_i32 v[84:85], s[26:27], s14, v84, 0
	v_add3_u32 v83, v83, v86, s37
	v_add3_u32 v81, v81, v87, s37
	v_lshl_add_u64 v[84:85], v[84:85], 1, s[12:13]
	v_and_b32_e32 v83, 0xffff0000, v83
	v_and_b32_e32 v86, 0xffff0000, v81
	v_lshl_add_u64 v[84:85], v[84:85], 0, v[0:1]
	v_or_b32_sdwa v81, v83, v82 dst_sel:DWORD dst_unused:UNUSED_PAD src0_sel:DWORD src1_sel:WORD_1
	v_or_b32_sdwa v80, v86, v80 dst_sel:DWORD dst_unused:UNUSED_PAD src0_sel:DWORD src1_sel:WORD_1
	global_store_dwordx2 v[84:85], v[80:81], off
	v_and_b32_sdwa v80, v78, v183 dst_sel:DWORD dst_unused:UNUSED_PAD src0_sel:WORD_1 src1_sel:DWORD
	v_and_b32_sdwa v81, v76, v183 dst_sel:DWORD dst_unused:UNUSED_PAD src0_sel:WORD_1 src1_sel:DWORD
	v_add3_u32 v76, v76, v81, s37
	v_add3_u32 v78, v78, v80, s37
	v_and_b32_sdwa v80, v79, v183 dst_sel:DWORD dst_unused:UNUSED_PAD src0_sel:WORD_1 src1_sel:DWORD
	v_and_b32_sdwa v81, v77, v183 dst_sel:DWORD dst_unused:UNUSED_PAD src0_sel:WORD_1 src1_sel:DWORD
	v_add3_u32 v79, v79, v80, s37
	v_add3_u32 v77, v77, v81, s37
	v_and_b32_e32 v79, 0xffff0000, v79
	v_and_b32_e32 v80, 0xffff0000, v77
	v_or_b32_sdwa v77, v79, v78 dst_sel:DWORD dst_unused:UNUSED_PAD src0_sel:DWORD src1_sel:WORD_1
	v_or_b32_sdwa v76, v80, v76 dst_sel:DWORD dst_unused:UNUSED_PAD src0_sel:DWORD src1_sel:WORD_1
	global_store_dwordx2 v[84:85], v[76:77], off offset:32
	v_and_b32_sdwa v76, v74, v183 dst_sel:DWORD dst_unused:UNUSED_PAD src0_sel:WORD_1 src1_sel:DWORD
	v_and_b32_sdwa v77, v72, v183 dst_sel:DWORD dst_unused:UNUSED_PAD src0_sel:WORD_1 src1_sel:DWORD
	v_add3_u32 v72, v72, v77, s37
	v_add3_u32 v74, v74, v76, s37
	v_and_b32_sdwa v76, v75, v183 dst_sel:DWORD dst_unused:UNUSED_PAD src0_sel:WORD_1 src1_sel:DWORD
	v_and_b32_sdwa v77, v73, v183 dst_sel:DWORD dst_unused:UNUSED_PAD src0_sel:WORD_1 src1_sel:DWORD
	v_add3_u32 v75, v75, v76, s37
	v_add3_u32 v73, v73, v77, s37
	v_and_b32_e32 v75, 0xffff0000, v75
	v_and_b32_e32 v76, 0xffff0000, v73
	v_or_b32_sdwa v73, v75, v74 dst_sel:DWORD dst_unused:UNUSED_PAD src0_sel:DWORD src1_sel:WORD_1
	v_or_b32_sdwa v72, v76, v72 dst_sel:DWORD dst_unused:UNUSED_PAD src0_sel:DWORD src1_sel:WORD_1
	global_store_dwordx2 v[84:85], v[72:73], off offset:64
	v_and_b32_sdwa v72, v70, v183 dst_sel:DWORD dst_unused:UNUSED_PAD src0_sel:WORD_1 src1_sel:DWORD
	v_and_b32_sdwa v73, v68, v183 dst_sel:DWORD dst_unused:UNUSED_PAD src0_sel:WORD_1 src1_sel:DWORD
	v_add3_u32 v68, v68, v73, s37
	v_add3_u32 v70, v70, v72, s37
	v_and_b32_sdwa v72, v71, v183 dst_sel:DWORD dst_unused:UNUSED_PAD src0_sel:WORD_1 src1_sel:DWORD
	v_and_b32_sdwa v73, v69, v183 dst_sel:DWORD dst_unused:UNUSED_PAD src0_sel:WORD_1 src1_sel:DWORD
	v_add3_u32 v71, v71, v72, s37
	v_add3_u32 v69, v69, v73, s37
	v_and_b32_e32 v71, 0xffff0000, v71
	v_and_b32_e32 v72, 0xffff0000, v69
	v_or_b32_sdwa v69, v71, v70 dst_sel:DWORD dst_unused:UNUSED_PAD src0_sel:DWORD src1_sel:WORD_1
	v_or_b32_sdwa v68, v72, v68 dst_sel:DWORD dst_unused:UNUSED_PAD src0_sel:DWORD src1_sel:WORD_1
	v_and_b32_sdwa v70, v66, v183 dst_sel:DWORD dst_unused:UNUSED_PAD src0_sel:WORD_1 src1_sel:DWORD
	v_and_b32_sdwa v71, v64, v183 dst_sel:DWORD dst_unused:UNUSED_PAD src0_sel:WORD_1 src1_sel:DWORD
	global_store_dwordx2 v[84:85], v[68:69], off offset:96
	v_or_b32_e32 v68, 64, v2
	v_add3_u32 v64, v64, v71, s37
	v_add3_u32 v66, v66, v70, s37
; __device__ __forceinline__ unsigned pack2(float a, float b) { return (unsigned)f2bf(a) | ((unsigned)f2bf(b) << 16); }
; __device__ __forceinline__ void phase_gemm_in(const Params& p, char* smem) {
;     ...
; #pragma unroll
;     for (int i = 0; i < 8; ++i) {
;       const int m = mt * 256 + wm * 128 + i * 16 + (lane & 15);
; #pragma unroll
;       for (int j = 0; j < 4; ++j) {
;         const int n = ncol0 + wn * 64 + j * 16 + (lane >> 4) * 4;
;         uint2 o;
;         o.x = pack2(acc[i][j][0], acc[i][j][1]);
;         o.y = pack2(acc[i][j][2], acc[i][j][3]);
;         *(uint2*)(dst + (size_t)m * ldd + n) = o;
;       }
;     }
	v_and_b32_sdwa v70, v67, v183 dst_sel:DWORD dst_unused:UNUSED_PAD src0_sel:WORD_1 src1_sel:DWORD
	v_and_b32_sdwa v71, v65, v183 dst_sel:DWORD dst_unused:UNUSED_PAD src0_sel:WORD_1 src1_sel:DWORD
	v_mad_i64_i32 v[68:69], s[26:27], s14, v68, 0
	v_add3_u32 v67, v67, v70, s37
	v_add3_u32 v65, v65, v71, s37
	v_lshl_add_u64 v[68:69], v[68:69], 1, s[12:13]
	v_and_b32_e32 v67, 0xffff0000, v67
	v_and_b32_e32 v70, 0xffff0000, v65
	v_lshl_add_u64 v[68:69], v[68:69], 0, v[0:1]
	v_or_b32_sdwa v65, v67, v66 dst_sel:DWORD dst_unused:UNUSED_PAD src0_sel:DWORD src1_sel:WORD_1
	v_or_b32_sdwa v64, v70, v64 dst_sel:DWORD dst_unused:UNUSED_PAD src0_sel:DWORD src1_sel:WORD_1
	global_store_dwordx2 v[68:69], v[64:65], off
	v_and_b32_sdwa v64, v62, v183 dst_sel:DWORD dst_unused:UNUSED_PAD src0_sel:WORD_1 src1_sel:DWORD
	v_and_b32_sdwa v65, v60, v183 dst_sel:DWORD dst_unused:UNUSED_PAD src0_sel:WORD_1 src1_sel:DWORD
	v_add3_u32 v60, v60, v65, s37
	v_add3_u32 v62, v62, v64, s37
	v_and_b32_sdwa v64, v63, v183 dst_sel:DWORD dst_unused:UNUSED_PAD src0_sel:WORD_1 src1_sel:DWORD
	v_and_b32_sdwa v65, v61, v183 dst_sel:DWORD dst_unused:UNUSED_PAD src0_sel:WORD_1 src1_sel:DWORD
	v_add3_u32 v63, v63, v64, s37
	v_add3_u32 v61, v61, v65, s37
	v_and_b32_e32 v63, 0xffff0000, v63
	v_and_b32_e32 v64, 0xffff0000, v61
	v_or_b32_sdwa v61, v63, v62 dst_sel:DWORD dst_unused:UNUSED_PAD src0_sel:DWORD src1_sel:WORD_1
	v_or_b32_sdwa v60, v64, v60 dst_sel:DWORD dst_unused:UNUSED_PAD src0_sel:DWORD src1_sel:WORD_1
	global_store_dwordx2 v[68:69], v[60:61], off offset:32
	v_and_b32_sdwa v60, v58, v183 dst_sel:DWORD dst_unused:UNUSED_PAD src0_sel:WORD_1 src1_sel:DWORD
	v_and_b32_sdwa v61, v56, v183 dst_sel:DWORD dst_unused:UNUSED_PAD src0_sel:WORD_1 src1_sel:DWORD
	v_add3_u32 v56, v56, v61, s37
	v_add3_u32 v58, v58, v60, s37
	v_and_b32_sdwa v60, v59, v183 dst_sel:DWORD dst_unused:UNUSED_PAD src0_sel:WORD_1 src1_sel:DWORD
	v_and_b32_sdwa v61, v57, v183 dst_sel:DWORD dst_unused:UNUSED_PAD src0_sel:WORD_1 src1_sel:DWORD
	v_add3_u32 v59, v59, v60, s37
	v_add3_u32 v57, v57, v61, s37
	v_and_b32_e32 v59, 0xffff0000, v59
	v_and_b32_e32 v60, 0xffff0000, v57
	v_or_b32_sdwa v57, v59, v58 dst_sel:DWORD dst_unused:UNUSED_PAD src0_sel:DWORD src1_sel:WORD_1
	v_or_b32_sdwa v56, v60, v56 dst_sel:DWORD dst_unused:UNUSED_PAD src0_sel:DWORD src1_sel:WORD_1
	global_store_dwordx2 v[68:69], v[56:57], off offset:64
	v_and_b32_sdwa v56, v54, v183 dst_sel:DWORD dst_unused:UNUSED_PAD src0_sel:WORD_1 src1_sel:DWORD
	v_and_b32_sdwa v57, v52, v183 dst_sel:DWORD dst_unused:UNUSED_PAD src0_sel:WORD_1 src1_sel:DWORD
	v_add3_u32 v52, v52, v57, s37
	v_add3_u32 v54, v54, v56, s37
	v_and_b32_sdwa v56, v55, v183 dst_sel:DWORD dst_unused:UNUSED_PAD src0_sel:WORD_1 src1_sel:DWORD
	v_and_b32_sdwa v57, v53, v183 dst_sel:DWORD dst_unused:UNUSED_PAD src0_sel:WORD_1 src1_sel:DWORD
	v_add3_u32 v55, v55, v56, s37
	v_add3_u32 v53, v53, v57, s37
	v_and_b32_e32 v55, 0xffff0000, v55
	v_and_b32_e32 v56, 0xffff0000, v53
	v_or_b32_sdwa v53, v55, v54 dst_sel:DWORD dst_unused:UNUSED_PAD src0_sel:DWORD src1_sel:WORD_1
	v_or_b32_sdwa v52, v56, v52 dst_sel:DWORD dst_unused:UNUSED_PAD src0_sel:DWORD src1_sel:WORD_1
	v_and_b32_sdwa v54, v50, v183 dst_sel:DWORD dst_unused:UNUSED_PAD src0_sel:WORD_1 src1_sel:DWORD
	v_and_b32_sdwa v55, v48, v183 dst_sel:DWORD dst_unused:UNUSED_PAD src0_sel:WORD_1 src1_sel:DWORD
	global_store_dwordx2 v[68:69], v[52:53], off offset:96
	v_or_b32_e32 v52, 0x50, v2
	v_add3_u32 v48, v48, v55, s37
	v_add3_u32 v50, v50, v54, s37
	v_and_b32_sdwa v54, v51, v183 dst_sel:DWORD dst_unused:UNUSED_PAD src0_sel:WORD_1 src1_sel:DWORD
	v_and_b32_sdwa v55, v49, v183 dst_sel:DWORD dst_unused:UNUSED_PAD src0_sel:WORD_1 src1_sel:DWORD
	v_mad_i64_i32 v[52:53], s[26:27], s14, v52, 0
	v_add3_u32 v51, v51, v54, s37
	v_add3_u32 v49, v49, v55, s37
	v_lshl_add_u64 v[52:53], v[52:53], 1, s[12:13]
	v_and_b32_e32 v51, 0xffff0000, v51
	v_and_b32_e32 v54, 0xffff0000, v49
	v_lshl_add_u64 v[52:53], v[52:53], 0, v[0:1]
	v_or_b32_sdwa v49, v51, v50 dst_sel:DWORD dst_unused:UNUSED_PAD src0_sel:DWORD src1_sel:WORD_1
	v_or_b32_sdwa v48, v54, v48 dst_sel:DWORD dst_unused:UNUSED_PAD src0_sel:DWORD src1_sel:WORD_1
	global_store_dwordx2 v[52:53], v[48:49], off
	v_and_b32_sdwa v48, v46, v183 dst_sel:DWORD dst_unused:UNUSED_PAD src0_sel:WORD_1 src1_sel:DWORD
	v_and_b32_sdwa v49, v44, v183 dst_sel:DWORD dst_unused:UNUSED_PAD src0_sel:WORD_1 src1_sel:DWORD
	v_add3_u32 v44, v44, v49, s37
	v_add3_u32 v46, v46, v48, s37
	v_and_b32_sdwa v48, v47, v183 dst_sel:DWORD dst_unused:UNUSED_PAD src0_sel:WORD_1 src1_sel:DWORD
	v_and_b32_sdwa v49, v45, v183 dst_sel:DWORD dst_unused:UNUSED_PAD src0_sel:WORD_1 src1_sel:DWORD
	v_add3_u32 v47, v47, v48, s37
	v_add3_u32 v45, v45, v49, s37
	v_and_b32_e32 v47, 0xffff0000, v47
	v_and_b32_e32 v48, 0xffff0000, v45
	v_or_b32_sdwa v45, v47, v46 dst_sel:DWORD dst_unused:UNUSED_PAD src0_sel:DWORD src1_sel:WORD_1
	v_or_b32_sdwa v44, v48, v44 dst_sel:DWORD dst_unused:UNUSED_PAD src0_sel:DWORD src1_sel:WORD_1
	global_store_dwordx2 v[52:53], v[44:45], off offset:32
	v_and_b32_sdwa v44, v42, v183 dst_sel:DWORD dst_unused:UNUSED_PAD src0_sel:WORD_1 src1_sel:DWORD
	v_and_b32_sdwa v45, v40, v183 dst_sel:DWORD dst_unused:UNUSED_PAD src0_sel:WORD_1 src1_sel:DWORD
	v_add3_u32 v40, v40, v45, s37
	v_add3_u32 v42, v42, v44, s37
	v_and_b32_sdwa v44, v43, v183 dst_sel:DWORD dst_unused:UNUSED_PAD src0_sel:WORD_1 src1_sel:DWORD
	v_and_b32_sdwa v45, v41, v183 dst_sel:DWORD dst_unused:UNUSED_PAD src0_sel:WORD_1 src1_sel:DWORD
	v_add3_u32 v43, v43, v44, s37
	v_add3_u32 v41, v41, v45, s37
	v_and_b32_e32 v43, 0xffff0000, v43
	v_and_b32_e32 v44, 0xffff0000, v41
; __device__ __forceinline__ unsigned pack2(float a, float b) { return (unsigned)f2bf(a) | ((unsigned)f2bf(b) << 16); }
; __device__ __forceinline__ void phase_gemm_in(const Params& p, char* smem) {
;     ...
; #pragma unroll
;     for (int i = 0; i < 8; ++i) {
;       const int m = mt * 256 + wm * 128 + i * 16 + (lane & 15);
; #pragma unroll
;       for (int j = 0; j < 4; ++j) {
;         const int n = ncol0 + wn * 64 + j * 16 + (lane >> 4) * 4;
;         uint2 o;
;         o.x = pack2(acc[i][j][0], acc[i][j][1]);
;         o.y = pack2(acc[i][j][2], acc[i][j][3]);
;         *(uint2*)(dst + (size_t)m * ldd + n) = o;
;       }
;     }
	v_or_b32_sdwa v41, v43, v42 dst_sel:DWORD dst_unused:UNUSED_PAD src0_sel:DWORD src1_sel:WORD_1
	v_or_b32_sdwa v40, v44, v40 dst_sel:DWORD dst_unused:UNUSED_PAD src0_sel:DWORD src1_sel:WORD_1
	global_store_dwordx2 v[52:53], v[40:41], off offset:64
	v_and_b32_sdwa v40, v38, v183 dst_sel:DWORD dst_unused:UNUSED_PAD src0_sel:WORD_1 src1_sel:DWORD
	v_and_b32_sdwa v41, v36, v183 dst_sel:DWORD dst_unused:UNUSED_PAD src0_sel:WORD_1 src1_sel:DWORD
	v_add3_u32 v36, v36, v41, s37
	v_add3_u32 v38, v38, v40, s37
	v_and_b32_sdwa v40, v39, v183 dst_sel:DWORD dst_unused:UNUSED_PAD src0_sel:WORD_1 src1_sel:DWORD
	v_and_b32_sdwa v41, v37, v183 dst_sel:DWORD dst_unused:UNUSED_PAD src0_sel:WORD_1 src1_sel:DWORD
	v_add3_u32 v39, v39, v40, s37
	v_add3_u32 v37, v37, v41, s37
	v_and_b32_e32 v39, 0xffff0000, v39
	v_and_b32_e32 v40, 0xffff0000, v37
	v_or_b32_sdwa v37, v39, v38 dst_sel:DWORD dst_unused:UNUSED_PAD src0_sel:DWORD src1_sel:WORD_1
	v_or_b32_sdwa v36, v40, v36 dst_sel:DWORD dst_unused:UNUSED_PAD src0_sel:DWORD src1_sel:WORD_1
	v_and_b32_sdwa v38, v34, v183 dst_sel:DWORD dst_unused:UNUSED_PAD src0_sel:WORD_1 src1_sel:DWORD
	v_and_b32_sdwa v39, v32, v183 dst_sel:DWORD dst_unused:UNUSED_PAD src0_sel:WORD_1 src1_sel:DWORD
	global_store_dwordx2 v[52:53], v[36:37], off offset:96
	v_or_b32_e32 v36, 0x60, v2
	v_add3_u32 v32, v32, v39, s37
	v_add3_u32 v34, v34, v38, s37
	v_and_b32_sdwa v38, v35, v183 dst_sel:DWORD dst_unused:UNUSED_PAD src0_sel:WORD_1 src1_sel:DWORD
	v_and_b32_sdwa v39, v33, v183 dst_sel:DWORD dst_unused:UNUSED_PAD src0_sel:WORD_1 src1_sel:DWORD
	v_mad_i64_i32 v[36:37], s[26:27], s14, v36, 0
	v_add3_u32 v35, v35, v38, s37
	v_add3_u32 v33, v33, v39, s37
	v_lshl_add_u64 v[36:37], v[36:37], 1, s[12:13]
	v_and_b32_e32 v35, 0xffff0000, v35
	v_and_b32_e32 v38, 0xffff0000, v33
	v_lshl_add_u64 v[36:37], v[36:37], 0, v[0:1]
	v_or_b32_sdwa v33, v35, v34 dst_sel:DWORD dst_unused:UNUSED_PAD src0_sel:DWORD src1_sel:WORD_1
	v_or_b32_sdwa v32, v38, v32 dst_sel:DWORD dst_unused:UNUSED_PAD src0_sel:DWORD src1_sel:WORD_1
	global_store_dwordx2 v[36:37], v[32:33], off
	v_and_b32_sdwa v32, v26, v183 dst_sel:DWORD dst_unused:UNUSED_PAD src0_sel:WORD_1 src1_sel:DWORD
	v_and_b32_sdwa v33, v24, v183 dst_sel:DWORD dst_unused:UNUSED_PAD src0_sel:WORD_1 src1_sel:DWORD
	v_add3_u32 v24, v24, v33, s37
	v_add3_u32 v26, v26, v32, s37
	v_and_b32_sdwa v32, v27, v183 dst_sel:DWORD dst_unused:UNUSED_PAD src0_sel:WORD_1 src1_sel:DWORD
	v_and_b32_sdwa v33, v25, v183 dst_sel:DWORD dst_unused:UNUSED_PAD src0_sel:WORD_1 src1_sel:DWORD
	v_add3_u32 v27, v27, v32, s37
	v_add3_u32 v25, v25, v33, s37
	v_and_b32_e32 v27, 0xffff0000, v27
	v_and_b32_e32 v32, 0xffff0000, v25
	v_or_b32_sdwa v25, v27, v26 dst_sel:DWORD dst_unused:UNUSED_PAD src0_sel:DWORD src1_sel:WORD_1
	v_or_b32_sdwa v24, v32, v24 dst_sel:DWORD dst_unused:UNUSED_PAD src0_sel:DWORD src1_sel:WORD_1
	global_store_dwordx2 v[36:37], v[24:25], off offset:32
	v_and_b32_sdwa v24, v22, v183 dst_sel:DWORD dst_unused:UNUSED_PAD src0_sel:WORD_1 src1_sel:DWORD
	v_and_b32_sdwa v25, v20, v183 dst_sel:DWORD dst_unused:UNUSED_PAD src0_sel:WORD_1 src1_sel:DWORD
	v_add3_u32 v20, v20, v25, s37
	v_add3_u32 v22, v22, v24, s37
	v_and_b32_sdwa v24, v23, v183 dst_sel:DWORD dst_unused:UNUSED_PAD src0_sel:WORD_1 src1_sel:DWORD
	v_and_b32_sdwa v25, v21, v183 dst_sel:DWORD dst_unused:UNUSED_PAD src0_sel:WORD_1 src1_sel:DWORD
	v_add3_u32 v23, v23, v24, s37
	v_add3_u32 v21, v21, v25, s37
	v_and_b32_e32 v23, 0xffff0000, v23
	v_and_b32_e32 v24, 0xffff0000, v21
	v_or_b32_sdwa v21, v23, v22 dst_sel:DWORD dst_unused:UNUSED_PAD src0_sel:DWORD src1_sel:WORD_1
	v_or_b32_sdwa v20, v24, v20 dst_sel:DWORD dst_unused:UNUSED_PAD src0_sel:DWORD src1_sel:WORD_1
	global_store_dwordx2 v[36:37], v[20:21], off offset:64
	v_and_b32_sdwa v20, v18, v183 dst_sel:DWORD dst_unused:UNUSED_PAD src0_sel:WORD_1 src1_sel:DWORD
	v_and_b32_sdwa v21, v16, v183 dst_sel:DWORD dst_unused:UNUSED_PAD src0_sel:WORD_1 src1_sel:DWORD
	v_add3_u32 v16, v16, v21, s37
	v_add3_u32 v18, v18, v20, s37
	v_and_b32_sdwa v20, v19, v183 dst_sel:DWORD dst_unused:UNUSED_PAD src0_sel:WORD_1 src1_sel:DWORD
; __device__ __forceinline__ unsigned pack2(float a, float b) { return (unsigned)f2bf(a) | ((unsigned)f2bf(b) << 16); }
; __device__ __forceinline__ void phase_gemm_in(const Params& p, char* smem) {
;     ...
; #pragma unroll
;     for (int i = 0; i < 8; ++i) {
;       const int m = mt * 256 + wm * 128 + i * 16 + (lane & 15);
; #pragma unroll
;       for (int j = 0; j < 4; ++j) {
;         const int n = ncol0 + wn * 64 + j * 16 + (lane >> 4) * 4;
;         uint2 o;
;         o.x = pack2(acc[i][j][0], acc[i][j][1]);
;         o.y = pack2(acc[i][j][2], acc[i][j][3]);
;         *(uint2*)(dst + (size_t)m * ldd + n) = o;
;       }
;     }
	v_and_b32_sdwa v21, v17, v183 dst_sel:DWORD dst_unused:UNUSED_PAD src0_sel:WORD_1 src1_sel:DWORD
	v_add3_u32 v19, v19, v20, s37
	v_add3_u32 v17, v17, v21, s37
	v_and_b32_e32 v19, 0xffff0000, v19
	v_and_b32_e32 v20, 0xffff0000, v17
	v_or_b32_sdwa v17, v19, v18 dst_sel:DWORD dst_unused:UNUSED_PAD src0_sel:DWORD src1_sel:WORD_1
	v_or_b32_sdwa v16, v20, v16 dst_sel:DWORD dst_unused:UNUSED_PAD src0_sel:DWORD src1_sel:WORD_1
	v_or_b32_e32 v2, 0x70, v2
	global_store_dwordx2 v[36:37], v[16:17], off offset:96
	v_mad_i64_i32 v[16:17], s[14:15], s14, v2, 0
	v_lshl_add_u64 v[16:17], v[16:17], 1, s[12:13]
	v_lshl_add_u64 v[0:1], v[16:17], 0, v[0:1]
	v_and_b32_sdwa v2, v14, v183 dst_sel:DWORD dst_unused:UNUSED_PAD src0_sel:WORD_1 src1_sel:DWORD
	v_and_b32_sdwa v16, v12, v183 dst_sel:DWORD dst_unused:UNUSED_PAD src0_sel:WORD_1 src1_sel:DWORD
	v_add3_u32 v12, v12, v16, s37
	v_add3_u32 v2, v14, v2, s37
	v_and_b32_sdwa v14, v15, v183 dst_sel:DWORD dst_unused:UNUSED_PAD src0_sel:WORD_1 src1_sel:DWORD
	v_and_b32_sdwa v16, v13, v183 dst_sel:DWORD dst_unused:UNUSED_PAD src0_sel:WORD_1 src1_sel:DWORD
	v_add3_u32 v14, v15, v14, s37
	v_add3_u32 v13, v13, v16, s37
	v_and_b32_e32 v14, 0xffff0000, v14
	v_and_b32_e32 v15, 0xffff0000, v13
	v_or_b32_sdwa v13, v14, v2 dst_sel:DWORD dst_unused:UNUSED_PAD src0_sel:DWORD src1_sel:WORD_1
	v_or_b32_sdwa v12, v15, v12 dst_sel:DWORD dst_unused:UNUSED_PAD src0_sel:DWORD src1_sel:WORD_1
	global_store_dwordx2 v[0:1], v[12:13], off
	v_and_b32_sdwa v2, v10, v183 dst_sel:DWORD dst_unused:UNUSED_PAD src0_sel:WORD_1 src1_sel:DWORD
	v_and_b32_sdwa v12, v8, v183 dst_sel:DWORD dst_unused:UNUSED_PAD src0_sel:WORD_1 src1_sel:DWORD
	v_add3_u32 v8, v8, v12, s37
	v_add3_u32 v2, v10, v2, s37
	v_and_b32_sdwa v10, v11, v183 dst_sel:DWORD dst_unused:UNUSED_PAD src0_sel:WORD_1 src1_sel:DWORD
	v_and_b32_sdwa v12, v9, v183 dst_sel:DWORD dst_unused:UNUSED_PAD src0_sel:WORD_1 src1_sel:DWORD
	v_add3_u32 v10, v11, v10, s37
	v_add3_u32 v9, v9, v12, s37
	v_and_b32_e32 v10, 0xffff0000, v10
	v_and_b32_e32 v11, 0xffff0000, v9
	v_or_b32_sdwa v9, v10, v2 dst_sel:DWORD dst_unused:UNUSED_PAD src0_sel:DWORD src1_sel:WORD_1
	v_or_b32_sdwa v8, v11, v8 dst_sel:DWORD dst_unused:UNUSED_PAD src0_sel:DWORD src1_sel:WORD_1
	global_store_dwordx2 v[0:1], v[8:9], off offset:32
	v_and_b32_sdwa v2, v6, v183 dst_sel:DWORD dst_unused:UNUSED_PAD src0_sel:WORD_1 src1_sel:DWORD
	v_and_b32_sdwa v8, v4, v183 dst_sel:DWORD dst_unused:UNUSED_PAD src0_sel:WORD_1 src1_sel:DWORD
	v_add3_u32 v4, v4, v8, s37
	v_add3_u32 v2, v6, v2, s37
	v_and_b32_sdwa v6, v7, v183 dst_sel:DWORD dst_unused:UNUSED_PAD src0_sel:WORD_1 src1_sel:DWORD
	v_and_b32_sdwa v8, v5, v183 dst_sel:DWORD dst_unused:UNUSED_PAD src0_sel:WORD_1 src1_sel:DWORD
	v_add3_u32 v6, v7, v6, s37
	v_add3_u32 v5, v5, v8, s37
	v_and_b32_e32 v6, 0xffff0000, v6
	v_and_b32_e32 v7, 0xffff0000, v5
	v_or_b32_sdwa v5, v6, v2 dst_sel:DWORD dst_unused:UNUSED_PAD src0_sel:DWORD src1_sel:WORD_1
	v_or_b32_sdwa v4, v7, v4 dst_sel:DWORD dst_unused:UNUSED_PAD src0_sel:DWORD src1_sel:WORD_1
	global_store_dwordx2 v[0:1], v[4:5], off offset:64
	v_and_b32_sdwa v5, v31, v183 dst_sel:DWORD dst_unused:UNUSED_PAD src0_sel:WORD_1 src1_sel:DWORD
	v_and_b32_sdwa v6, v29, v183 dst_sel:DWORD dst_unused:UNUSED_PAD src0_sel:WORD_1 src1_sel:DWORD
	v_and_b32_sdwa v2, v30, v183 dst_sel:DWORD dst_unused:UNUSED_PAD src0_sel:WORD_1 src1_sel:DWORD
	v_and_b32_sdwa v4, v28, v183 dst_sel:DWORD dst_unused:UNUSED_PAD src0_sel:WORD_1 src1_sel:DWORD
	v_add3_u32 v5, v31, v5, s37
	v_add3_u32 v6, v29, v6, s37
	s_add_i32 s23, s23, 1
	v_add3_u32 v4, v28, v4, s37
	v_add3_u32 v2, v30, v2, s37
	v_and_b32_e32 v5, 0xffff0000, v5
	v_and_b32_e32 v6, 0xffff0000, v6
	s_cmp_eq_u32 s23, s17
	v_or_b32_sdwa v5, v5, v2 dst_sel:DWORD dst_unused:UNUSED_PAD src0_sel:DWORD src1_sel:WORD_1
	v_or_b32_sdwa v4, v6, v4 dst_sel:DWORD dst_unused:UNUSED_PAD src0_sel:DWORD src1_sel:WORD_1
	s_cselect_b64 s[12:13], -1, 0
	s_mov_b32 s31, 0x18000
	global_store_dwordx2 v[0:1], v[4:5], off offset:96
	s_branch .LBB0_708
